# v49 + diff-attention K tile swizzled over 16 rows (ds_read_b128 bank conflict removed) + in-loop PREP/mask/row-max/alpha block of a wholly masked tile skipped (alpha=1, max unchanged)
# baseline (speedup 1.0000x reference)
.Lmskip_fox_1:
	s_sub_i32 s0, s11, s27
	s_cmp_ge_i32 s0, 95
	s_cbranch_scc1 .Lp1skip_fox_1
	ds_read_b128 v[66:69], v198
	ds_read_b128 v[70:73], v198 offset:32
	ds_read_b128 v[202:205], v198 offset:128
	ds_read_b128 v[206:209], v198 offset:160
	ds_read_b128 v[76:79], v198 offset:64
	ds_read_b128 v[210:213], v198 offset:96
	ds_read_b128 v[214:217], v198 offset:192
	ds_read_b128 v[220:223], v198 offset:224
	s_waitcnt lgkmcnt(7)
	s_waitcnt lgkmcnt(3)
	v_xor_b32_e32 v225, 0x80000000, v79
	v_xor_b32_e32 v224, 0x80000000, v78
	s_waitcnt lgkmcnt(2)
	v_fma_f32 v74, v110, s12, -v210
	v_fma_f32 v75, v111, s12, -v211
	v_fma_f32 v78, v106, s12, -v76
	v_fma_f32 v79, v107, s12, -v77
	v_fma_f32 v102, v102, s12, -v70
	v_fma_f32 v103, v103, s12, -v71
	v_fma_f32 v106, v108, s12, v224
	v_fma_f32 v107, v109, s12, v225
	v_xor_b32_e32 v109, 0x80000000, v205
	v_xor_b32_e32 v108, 0x80000000, v204
	v_xor_b32_e32 v111, 0x80000000, v209
	v_xor_b32_e32 v110, 0x80000000, v208
	s_waitcnt lgkmcnt(1)
	s_waitcnt lgkmcnt(0)
	v_fma_f32 v80, v112, s12, -v212
	v_fma_f32 v81, v113, s12, -v213
	v_fma_f32 v104, v104, s12, -v72
	v_fma_f32 v105, v105, s12, -v73
	v_fma_f32 v100, v100, s12, -v68
	v_fma_f32 v101, v101, s12, -v69
	v_fma_f32 v98, v98, s12, -v66
	v_fma_f32 v99, v99, s12, -v67
	v_fma_f32 v66, v94, s12, -v220
	v_fma_f32 v67, v95, s12, -v221
	v_fma_f32 v68, v90, s12, -v214
	v_fma_f32 v69, v91, s12, -v215
	v_fma_f32 v72, v86, s12, -v206
	v_fma_f32 v73, v87, s12, -v207
	v_fma_f32 v70, v96, s12, -v222
	v_fma_f32 v71, v97, s12, -v223
	v_fma_f32 v76, v92, s12, -v216
	v_fma_f32 v77, v93, s12, -v217
	v_fma_f32 v86, v88, s12, v110
	v_fma_f32 v87, v89, s12, v111
	v_fma_f32 v84, v84, s12, v108
	v_fma_f32 v85, v85, s12, v109
	s_cmp_le_i32 s11, s27
	v_fma_f32 v82, v82, s12, -v202
	v_fma_f32 v83, v83, s12, -v203
	s_cbranch_scc1 .LBB0_647
	v_add_u32_e32 v1, 64, v199
	v_cmp_gt_i32_e64 s[92:93], 26, v1
	v_cmp_gt_i32_e64 s[94:95], 27, v1
	v_cmp_gt_i32_e64 s[90:91], 25, v1
	s_and_b64 s[92:93], s[94:95], s[92:93]
	v_cmp_gt_i32_e64 s[88:89], 24, v1
	s_and_b64 s[90:91], s[92:93], s[90:91]
	v_cmp_gt_i32_e64 s[86:87], 19, v1
	s_and_b64 s[88:89], s[90:91], s[88:89]
	v_cmp_gt_i32_e64 s[84:85], 18, v1
	s_and_b64 s[86:87], s[88:89], s[86:87]
	v_cmp_gt_i32_e64 s[82:83], 17, v1
	s_and_b64 s[84:85], s[86:87], s[84:85]
	v_cmp_gt_i32_e64 s[80:81], 16, v1
	s_and_b64 s[82:83], s[84:85], s[82:83]
	v_cmp_gt_i32_e64 s[78:79], 11, v1
	s_and_b64 s[80:81], s[82:83], s[80:81]
	v_cmp_gt_i32_e64 s[76:77], 10, v1
	s_and_b64 s[78:79], s[80:81], s[78:79]
	v_cmp_gt_i32_e64 s[74:75], 9, v1
	s_and_b64 s[76:77], s[78:79], s[76:77]
	v_cmp_gt_i32_e64 s[72:73], 8, v1
	s_and_b64 s[74:75], s[76:77], s[74:75]
	v_cmp_gt_i32_e64 s[70:71], 3, v1
	s_and_b64 s[72:73], s[74:75], s[72:73]
	v_cmp_gt_i32_e64 s[68:69], 2, v1
	s_and_b64 s[70:71], s[72:73], s[70:71]
	v_cmp_gt_i32_e64 s[2:3], 1, v1
	s_and_b64 s[68:69], s[70:71], s[68:69]
	v_cmp_gt_i32_e64 s[0:1], 0, v1
	s_and_b64 s[2:3], s[68:69], s[2:3]
	s_and_b64 s[0:1], s[2:3], s[0:1]
	v_cmp_gt_i32_e64 s[66:67], 58, v1
	v_cndmask_b32_e64 v98, v98, v175, s[0:1]
	v_cmp_gt_i32_e64 s[0:1], 59, v1
	v_cmp_gt_i32_e64 s[64:65], 57, v1
	v_cmp_gt_i32_e64 s[62:63], 56, v1
	v_cndmask_b32_e64 v71, v71, v175, s[0:1]
	s_and_b64 s[0:1], s[0:1], s[66:67]
	v_cndmask_b32_e64 v70, v70, v175, s[0:1]
	s_and_b64 s[0:1], s[0:1], s[64:65]
	v_cmp_gt_i32_e64 s[60:61], 51, v1
	v_cndmask_b32_e64 v67, v67, v175, s[0:1]
	s_and_b64 s[0:1], s[0:1], s[62:63]
	v_cmp_gt_i32_e64 s[58:59], 50, v1
	v_cndmask_b32_e64 v66, v66, v175, s[0:1]
	s_and_b64 s[0:1], s[0:1], s[60:61]
	v_cmp_gt_i32_e64 s[56:57], 49, v1
	v_cndmask_b32_e64 v77, v77, v175, s[0:1]
	s_and_b64 s[0:1], s[0:1], s[58:59]
	v_cmp_gt_i32_e64 s[54:55], 48, v1
	v_cndmask_b32_e64 v76, v76, v175, s[0:1]
	s_and_b64 s[0:1], s[0:1], s[56:57]
	v_cmp_gt_i32_e64 s[52:53], 43, v1
	v_cndmask_b32_e64 v69, v69, v175, s[0:1]
	s_and_b64 s[0:1], s[0:1], s[54:55]
	v_cmp_gt_i32_e64 s[50:51], 42, v1
	v_cndmask_b32_e64 v68, v68, v175, s[0:1]
	s_and_b64 s[0:1], s[0:1], s[52:53]
	v_cmp_gt_i32_e64 s[48:49], 41, v1
	v_cndmask_b32_e64 v87, v87, v175, s[0:1]
	s_and_b64 s[0:1], s[0:1], s[50:51]
	v_cmp_gt_i32_e64 s[46:47], 40, v1
	v_cndmask_b32_e64 v86, v86, v175, s[0:1]
	s_and_b64 s[0:1], s[0:1], s[48:49]
	v_cmp_gt_i32_e64 s[44:45], 35, v1
	v_cndmask_b32_e64 v73, v73, v175, s[0:1]
	s_and_b64 s[0:1], s[0:1], s[46:47]
	v_cmp_gt_i32_e64 s[42:43], 34, v1
	v_cndmask_b32_e64 v72, v72, v175, s[0:1]
	s_and_b64 s[0:1], s[0:1], s[44:45]
	v_cmp_gt_i32_e64 s[40:41], 33, v1
	v_cndmask_b32_e64 v85, v85, v175, s[0:1]
	s_and_b64 s[0:1], s[0:1], s[42:43]
	v_cmp_gt_i32_e32 vcc, 32, v1
	v_cndmask_b32_e64 v84, v84, v175, s[0:1]
	s_and_b64 s[0:1], s[0:1], s[40:41]
	v_cndmask_b32_e64 v74, v74, v175, s[88:89]
	v_readlane_b32 s88, v242, 2
	s_and_b64 vcc, s[0:1], vcc
	v_cndmask_b32_e64 v81, v81, v175, s[94:95]
	v_cndmask_b32_e64 v80, v80, v175, s[92:93]
	s_movk_i32 s93, 0x6018
	s_mov_b32 s92, 0xf800000
	v_cndmask_b32_e64 v75, v75, v175, s[90:91]
	s_mov_b64 s[90:91], s[16:17]
	v_readlane_b32 s89, v242, 3
	v_cndmask_b32_e64 v107, v107, v175, s[86:87]
	v_readlane_b32 s86, v242, 0
	v_cndmask_b32_e64 v106, v106, v175, s[84:85]
	v_cndmask_b32_e64 v79, v79, v175, s[82:83]
	s_movk_i32 s83, 0x6000
	v_cndmask_b32_e64 v78, v78, v175, s[80:81]
	v_cndmask_b32_e64 v105, v105, v175, s[78:79]
	v_cndmask_b32_e64 v104, v104, v175, s[76:77]
	v_cndmask_b32_e64 v103, v103, v175, s[74:75]
	v_cndmask_b32_e64 v102, v102, v175, s[72:73]
	v_cndmask_b32_e64 v101, v101, v175, s[70:71]
	v_cndmask_b32_e64 v100, v100, v175, s[68:69]
	v_cndmask_b32_e64 v99, v99, v175, s[2:3]
	s_mov_b32 s56, s30
	v_cndmask_b32_e64 v83, v83, v175, s[0:1]
	v_cndmask_b32_e32 v82, v82, v175, vcc
	v_readlane_b32 s87, v242, 1

.Lp1join_fox_1:
	v_cmp_gt_f32_e32 vcc, 1.0, v108
	s_barrier
	s_waitcnt vmcnt(1)
	ds_write_b128 v193, v[154:157] offset:32768
	s_waitcnt vmcnt(0)
	ds_write_b128 v193, v[158:161] offset:40960
	ds_write_b128 v194, v[146:149]
	ds_write_b128 v195, v[150:153]
	s_cbranch_vccz .LBB0_651
	s_and_saveexec_b64 s[0:1], s[38:39]
	ds_write_b32 v185, v108 offset:128
	s_or_b64 exec, exec, s[0:1]
	s_waitcnt lgkmcnt(0)
	ds_read_b128 v[88:91], v184 offset:224
	ds_read_b128 v[92:95], v184 offset:192
	ds_read_b128 v[110:113], v184 offset:160
	ds_read_b128 v[202:205], v184 offset:128
	s_waitcnt lgkmcnt(3)
	v_mul_f32 v64, v64, v90
	v_mul_f32 v65, v65, v91
	s_waitcnt lgkmcnt(2)
	v_mul_f32 v60, v60, v94
	v_mul_f32 v61, v61, v95
	s_waitcnt lgkmcnt(1)
	v_mul_f32 v56, v56, v112
	v_mul_f32 v57, v57, v113
	s_waitcnt lgkmcnt(0)
	v_mul_f32 v52, v52, v204
	v_mul_f32 v53, v53, v205
	v_mul_f32 v62, v62, v88
	v_mul_f32 v63, v63, v89
	v_mul_f32 v58, v58, v92
	v_mul_f32 v59, v59, v93
	v_mul_f32 v54, v54, v110
	v_mul_f32 v55, v55, v111
	v_mul_f32 v50, v50, v202
	v_mul_f32 v51, v51, v203
	v_mul_f32 v48, v48, v90
	v_mul_f32 v49, v49, v91
	v_mul_f32 v44, v44, v94
	v_mul_f32 v45, v45, v95
	v_mul_f32 v40, v40, v112
	v_mul_f32 v41, v41, v113
	v_mul_f32 v36, v36, v204
	v_mul_f32 v37, v37, v205
	v_mul_f32 v46, v46, v88
	v_mul_f32 v47, v47, v89
	v_mul_f32 v42, v42, v92
	v_mul_f32 v43, v43, v93
	v_mul_f32 v38, v38, v110
	v_mul_f32 v39, v39, v111
	v_mul_f32 v34, v34, v202
	v_mul_f32 v35, v35, v203
	v_mul_f32 v32, v32, v90
	v_mul_f32 v33, v33, v91
	v_mul_f32 v28, v28, v94
	v_mul_f32 v29, v29, v95
	v_mul_f32 v24, v24, v112
	v_mul_f32 v25, v25, v113
	v_mul_f32 v20, v20, v204
	v_mul_f32 v21, v21, v205
	v_mul_f32 v30, v30, v88
	v_mul_f32 v31, v31, v89
	v_mul_f32 v26, v26, v92
	v_mul_f32 v27, v27, v93
	v_mul_f32 v22, v22, v110
	v_mul_f32 v23, v23, v111
	v_mul_f32 v18, v18, v202
	v_mul_f32 v19, v19, v203
	v_mul_f32 v16, v16, v90
	v_mul_f32 v17, v17, v91
	v_mul_f32 v12, v12, v94
	v_mul_f32 v13, v13, v95
	v_mul_f32 v8, v8, v112
	v_mul_f32 v9, v9, v113
	v_mul_f32 v4, v4, v204
	v_mul_f32 v5, v5, v205
	v_mul_f32 v14, v14, v88
	v_mul_f32 v15, v15, v89
	v_mul_f32 v10, v10, v92
	v_mul_f32 v11, v11, v93
	v_mul_f32 v6, v6, v110
	v_mul_f32 v7, v7, v111
	v_mul_f32 v2, v2, v202
	v_mul_f32 v3, v3, v203

.Lmskip_fox_3:
	s_sub_i32 s0, s11, s27
	s_cmp_ge_i32 s0, 31
	s_cbranch_scc1 .Lp1skip_fox_3
	ds_read_b128 v[100:103], v198 offset:256
	ds_read_b128 v[110:113], v198 offset:288
	ds_read_b128 v[202:205], v198 offset:384
	ds_read_b128 v[206:209], v198 offset:416
	ds_read_b128 v[210:213], v198 offset:320
	ds_read_b128 v[214:217], v198 offset:352
	ds_read_b128 v[218:221], v198 offset:448
	ds_read_b128 v[222:225], v198 offset:480
	s_waitcnt lgkmcnt(7)
	s_waitcnt lgkmcnt(6)
	v_xor_b32_e32 v107, 0x80000000, v113
	v_xor_b32_e32 v106, 0x80000000, v112
	s_waitcnt lgkmcnt(3)
	v_xor_b32_e32 v113, 0x80000000, v213
	v_xor_b32_e32 v112, 0x80000000, v212
	s_waitcnt lgkmcnt(2)
	v_xor_b32_e32 v213, 0x80000000, v217
	v_xor_b32_e32 v212, 0x80000000, v216
	v_fma_f32 v98, v86, s12, -v110
	v_fma_f32 v99, v87, s12, -v111
	v_fma_f32 v86, v96, s12, v212
	v_fma_f32 v87, v97, s12, v213
	v_fma_f32 v88, v88, s12, v106
	v_fma_f32 v89, v89, s12, v107
	v_fma_f32 v84, v84, s12, -v102
	v_fma_f32 v85, v85, s12, -v103
	v_fma_f32 v96, v82, s12, -v100
	v_fma_f32 v97, v83, s12, -v101
	s_waitcnt lgkmcnt(1)
	v_xor_b32_e32 v107, 0x80000000, v221
	v_xor_b32_e32 v106, 0x80000000, v220
	s_waitcnt lgkmcnt(0)
	v_xor_b32_e32 v111, 0x80000000, v225
	v_xor_b32_e32 v110, 0x80000000, v224
	s_add_i32 s0, s11, 64
	v_fma_f32 v94, v94, s12, -v214
	v_fma_f32 v95, v95, s12, -v215
	v_fma_f32 v90, v90, s12, -v210
	v_fma_f32 v91, v91, s12, -v211
	v_fma_f32 v92, v92, s12, v112
	v_fma_f32 v93, v93, s12, v113
	v_fma_f32 v82, v78, s12, -v222
	v_fma_f32 v83, v79, s12, -v223
	v_fma_f32 v74, v74, s12, -v218
	v_fma_f32 v75, v75, s12, -v219
	v_fma_f32 v78, v70, s12, -v206
	v_fma_f32 v79, v71, s12, -v207
	v_fma_f32 v70, v80, s12, v110
	v_fma_f32 v71, v81, s12, v111
	v_fma_f32 v76, v76, s12, v106
	v_fma_f32 v77, v77, s12, v107
	v_fma_f32 v100, v72, s12, -v208
	v_fma_f32 v101, v73, s12, -v209
	v_fma_f32 v102, v68, s12, -v204
	v_fma_f32 v103, v69, s12, -v205
	s_cmp_le_i32 s0, s27
	v_fma_f32 v80, v66, s12, -v202
	v_fma_f32 v81, v67, s12, -v203
	s_cbranch_scc1 .LBB0_655
	v_cmp_gt_i32_e64 s[92:93], 26, v199
	v_cmp_gt_i32_e64 s[94:95], 27, v199
	v_cmp_gt_i32_e64 s[90:91], 25, v199
	s_and_b64 s[92:93], s[94:95], s[92:93]
	v_cmp_gt_i32_e64 s[88:89], 24, v199
	s_and_b64 s[90:91], s[92:93], s[90:91]
	v_cmp_gt_i32_e64 s[86:87], 19, v199
	s_and_b64 s[88:89], s[90:91], s[88:89]
	v_cmp_gt_i32_e64 s[84:85], 18, v199
	s_and_b64 s[86:87], s[88:89], s[86:87]
	v_cmp_gt_i32_e64 s[82:83], 17, v199
	s_and_b64 s[84:85], s[86:87], s[84:85]
	v_cmp_gt_i32_e64 s[80:81], 16, v199
	s_and_b64 s[82:83], s[84:85], s[82:83]
	v_cmp_gt_i32_e64 s[78:79], 11, v199
	s_and_b64 s[80:81], s[82:83], s[80:81]
	v_cmp_gt_i32_e64 s[76:77], 10, v199
	s_and_b64 s[78:79], s[80:81], s[78:79]
	v_cmp_gt_i32_e64 s[74:75], 9, v199
	s_and_b64 s[76:77], s[78:79], s[76:77]
	v_cmp_gt_i32_e64 s[72:73], 8, v199
	s_and_b64 s[74:75], s[76:77], s[74:75]
	v_cmp_gt_i32_e64 s[70:71], 3, v199
	s_and_b64 s[72:73], s[74:75], s[72:73]
	v_cmp_gt_i32_e64 s[68:69], 2, v199
	s_and_b64 s[70:71], s[72:73], s[70:71]
	v_cmp_gt_i32_e64 s[2:3], 1, v199
	s_and_b64 s[68:69], s[70:71], s[68:69]
	v_cmp_gt_i32_e64 s[0:1], 0, v199
	s_and_b64 s[2:3], s[68:69], s[2:3]
	s_and_b64 s[0:1], s[2:3], s[0:1]
	v_cmp_gt_i32_e64 s[66:67], 58, v199
	v_cndmask_b32_e64 v96, v96, v175, s[0:1]
	v_cmp_gt_i32_e64 s[0:1], 59, v199
	v_cmp_gt_i32_e64 s[64:65], 57, v199
	v_cmp_gt_i32_e64 s[62:63], 56, v199
	v_cndmask_b32_e64 v71, v71, v175, s[0:1]
	s_and_b64 s[0:1], s[0:1], s[66:67]
	v_cndmask_b32_e64 v70, v70, v175, s[0:1]
	s_and_b64 s[0:1], s[0:1], s[64:65]
	v_cmp_gt_i32_e64 s[60:61], 51, v199
	v_cndmask_b32_e64 v83, v83, v175, s[0:1]
	s_and_b64 s[0:1], s[0:1], s[62:63]
	v_cmp_gt_i32_e64 s[58:59], 50, v199
	v_cndmask_b32_e64 v82, v82, v175, s[0:1]
	s_and_b64 s[0:1], s[0:1], s[60:61]
	v_cmp_gt_i32_e64 s[56:57], 49, v199
	v_cndmask_b32_e64 v77, v77, v175, s[0:1]
	s_and_b64 s[0:1], s[0:1], s[58:59]
	v_cmp_gt_i32_e64 s[54:55], 48, v199
	v_cndmask_b32_e64 v76, v76, v175, s[0:1]
	s_and_b64 s[0:1], s[0:1], s[56:57]
	v_cmp_gt_i32_e64 s[52:53], 43, v199
	v_cndmask_b32_e64 v75, v75, v175, s[0:1]
	s_and_b64 s[0:1], s[0:1], s[54:55]
	v_cmp_gt_i32_e64 s[50:51], 42, v199
	v_cndmask_b32_e64 v74, v74, v175, s[0:1]
	s_and_b64 s[0:1], s[0:1], s[52:53]
	v_cmp_gt_i32_e64 s[48:49], 41, v199
	v_cndmask_b32_e64 v101, v101, v175, s[0:1]
	s_and_b64 s[0:1], s[0:1], s[50:51]
	v_cmp_gt_i32_e64 s[46:47], 40, v199
	v_cndmask_b32_e64 v100, v100, v175, s[0:1]
	s_and_b64 s[0:1], s[0:1], s[48:49]
	v_cmp_gt_i32_e64 s[44:45], 35, v199
	v_cndmask_b32_e64 v79, v79, v175, s[0:1]
	s_and_b64 s[0:1], s[0:1], s[46:47]
	v_cmp_gt_i32_e64 s[42:43], 34, v199
	v_cndmask_b32_e64 v78, v78, v175, s[0:1]
	s_and_b64 s[0:1], s[0:1], s[44:45]
	v_cmp_gt_i32_e64 s[40:41], 33, v199
	v_cndmask_b32_e64 v103, v103, v175, s[0:1]
	s_and_b64 s[0:1], s[0:1], s[42:43]
	v_cmp_gt_i32_e32 vcc, 32, v199
	v_cndmask_b32_e64 v102, v102, v175, s[0:1]
	s_and_b64 s[0:1], s[0:1], s[40:41]
	v_cndmask_b32_e64 v94, v94, v175, s[88:89]
	v_readlane_b32 s88, v242, 2
	s_and_b64 vcc, s[0:1], vcc
	v_cndmask_b32_e64 v87, v87, v175, s[94:95]
	v_cndmask_b32_e64 v86, v86, v175, s[92:93]
	s_movk_i32 s93, 0x6018
	s_mov_b32 s92, 0xf800000
	v_cndmask_b32_e64 v95, v95, v175, s[90:91]
	s_mov_b64 s[90:91], s[16:17]
	v_readlane_b32 s89, v242, 3
	v_cndmask_b32_e64 v93, v93, v175, s[86:87]
	v_readlane_b32 s86, v242, 0
	v_cndmask_b32_e64 v92, v92, v175, s[84:85]
	v_cndmask_b32_e64 v91, v91, v175, s[82:83]
	s_movk_i32 s83, 0x6000
	v_cndmask_b32_e64 v90, v90, v175, s[80:81]
	v_cndmask_b32_e64 v89, v89, v175, s[78:79]
	v_cndmask_b32_e64 v88, v88, v175, s[76:77]
	v_cndmask_b32_e64 v99, v99, v175, s[74:75]
	v_cndmask_b32_e64 v98, v98, v175, s[72:73]
	v_cndmask_b32_e64 v85, v85, v175, s[70:71]
	v_cndmask_b32_e64 v84, v84, v175, s[68:69]
	v_cndmask_b32_e64 v97, v97, v175, s[2:3]
	s_mov_b32 s56, s30
	v_cndmask_b32_e64 v81, v81, v175, s[0:1]
	v_cndmask_b32_e32 v80, v80, v175, vcc
	v_readlane_b32 s87, v242, 1

.Lp1join_fox_3:
	s_andn2_b64 vcc, exec, s[22:23]
	s_barrier
	s_cbranch_vccnz .LBB0_657
	s_waitcnt vmcnt(1)
	ds_write_b128 v193, v[154:157] offset:49152
	s_waitcnt vmcnt(0)
	ds_write_b128 v193, v[158:161] offset:57344
	ds_write_b128 v194, v[146:149] offset:16384
	ds_write_b128 v195, v[150:153] offset:16384

.Lp1skip_fox_1:
	v_mov_b32_e32 v108, 1.0
	s_mov_b64 s[40:41], -1
	s_branch .Lp1join_fox_1
.Lp1skip_fox_3:
	s_mov_b64 s[40:41], -1
	s_branch .Lp1join_fox_3

.LBB0_819:
	s_or_b64 exec, exec, s[0:1]
	s_abs_i32 s0, s13
	v_readlane_b32 s1, v243, 2
	s_mul_hi_u32 s1, s0, s1
	v_readlane_b32 s18, v243, 1
	s_mul_i32 s2, s1, s18
	s_sub_i32 s0, s0, s2
	s_ashr_i32 s9, s13, 31
	s_add_i32 s2, s1, 1
	s_sub_i32 s3, s0, s18
	s_cmp_ge_u32 s0, s18
	s_cselect_b32 s1, s2, s1
	s_cselect_b32 s0, s3, s0
	s_add_i32 s2, s1, 1
	s_cmp_ge_u32 s0, s18
	s_cselect_b32 s0, s2, s1
	s_xor_b32 s11, s0, s9
	s_sub_i32 s8, s11, s9
	s_mul_i32 s0, s8, s18
	v_readlane_b32 s1, v245, 13
	s_sub_i32 s0, s13, s0
	s_mul_i32 s1, s18, s1
	s_add_i32 s0, s0, s1
	s_ashr_i32 s1, s0, 31
	s_lshr_b32 s1, s1, 29
	s_add_i32 s1, s0, s1
	s_ashr_i32 s20, s1, 3
	s_and_b32 s1, s1, -8
	s_lshl_b32 s3, s8, 8
	s_sub_i32 s28, s0, s1
	s_ashr_i32 s21, s20, 31
	s_sub_i32 s3, 0x700, s3
	s_and_b32 s2, s28, 1
	s_lshl_b64 s[0:1], s[20:21], 11
	s_ashr_i32 s13, s3, 31
	s_add_u32 s18, s0, s3
	s_addc_u32 s19, s1, s13
	s_mul_i32 s0, s19, 0x3000
	s_mul_hi_u32 s1, s18, 0x3000
	s_add_i32 s1, s1, s0
	s_mul_i32 s0, s18, 0x3000
	v_readlane_b32 s25, v245, 14
	s_add_u32 s13, s25, s0
	v_readlane_b32 s26, v245, 15
	s_addc_u32 s21, s26, s1
	s_lshl_b32 s0, s28, 6
	s_and_b32 s0, s0, 0xffffff80
	s_ashr_i32 s1, s0, 31
	s_lshl_b64 s[22:23], s[0:1], 1
	s_add_u32 s0, s13, s22
	s_addc_u32 s1, s21, s23
	s_lshl_b32 s2, s2, 7
	v_mov_b32_e32 v150, v0
	s_add_u32 s0, s0, s2
	s_addc_u32 s1, s1, 0
	s_waitcnt vmcnt(8)
	v_ashrrev_i32_e32 v158, 4, v150
	s_mul_hi_i32 s13, s20, 0x1800000
	s_mul_i32 s20, s20, 0x1800000
	v_lshlrev_b32_e32 v2, 3, v150
	v_and_b32_e32 v4, 0xfffff0, v158
	v_lshlrev_b32_e32 v5, 1, v158
	s_add_u32 s20, s25, s20
	v_and_b32_e32 v3, 0x78, v2
	v_and_or_b32 v4, v5, 8, v4
	v_lshrrev_b32_e32 v5, 1, v158
	v_and_b32_e32 v6, 3, v158
	v_add_u32_e32 v8, 32, v158
	s_addc_u32 s13, s26, s13
	v_and_or_b32 v5, v5, 4, v6
	v_lshlrev_b32_e32 v50, 1, v3
	v_and_b32_e32 v3, 0xfffff0, v8
	v_lshlrev_b32_e32 v6, 1, v8
	s_add_u32 s22, s20, s22
	v_and_or_b32 v3, v6, 8, v3
	s_addc_u32 s23, s13, s23
	v_readfirstlane_b32 s13, v150
	v_lshrrev_b32_e32 v4, 1, v4
	v_bfe_u32 v2, v2, 5, 2
	v_lshrrev_b32_e32 v3, 1, v3
	s_ashr_i32 s29, s13, 6
	v_or_b32_e32 v4, v4, v2
	v_or_b32_e32 v2, v3, v2
	v_and_b32_e32 v151, 31, v150
	v_lshlrev_b32_e32 v6, 9, v2
	v_lshlrev_b32_e32 v2, 8, v158
	v_and_b32_e32 v3, 0xf0, v150
	s_lshl_b32 s34, s29, 5
	v_bfe_u32 v152, v150, 5, 1
	v_bitop3_b32 v20, v50, v2, v3 bitop3:0xde
	v_or_b32_e32 v7, s34, v151
	v_mov_b64_e32 v[2:3], s[0:1]
	v_mad_i64_i32 v[2:3], s[0:1], v7, s33, v[2:3]
	v_lshlrev_b32_e32 v162, 4, v152
	v_lshl_add_u64 v[2:3], v[2:3], 0, v[162:163]
	v_lshlrev_b32_e32 v4, 9, v4
	v_lshlrev_b32_e32 v5, 6, v5
	global_load_dwordx4 v[110:113], v[2:3], off
	global_load_dwordx4 v[106:109], v[2:3], off offset:32
	global_load_dwordx4 v[102:105], v[2:3], off offset:64
	global_load_dwordx4 v[98:101], v[2:3], off offset:96
	v_and_b32_e32 v2, 48, v50
	v_lshlrev_b32_e32 v52, 2, v152
	v_or3_b32 v21, v4, v5, v2
	v_or3_b32 v22, v6, v5, v2
	s_add_i32 s25, s34, s3
	v_sub_u32_e32 v2, v151, v52
	v_add_u32_e32 v156, s25, v2
	v_mov_b64_e32 v[2:3], s[22:23]
	v_mad_i64_i32 v[4:5], s[0:1], v158, s33, v[2:3]
	v_mov_b32_e32 v51, v163
	v_mad_i64_i32 v[8:9], s[0:1], v8, s33, v[2:3]
	v_lshl_add_u64 v[12:13], v[4:5], 0, v[50:51]
	v_lshl_add_u64 v[16:17], v[8:9], 0, v[50:51]
	global_load_dwordx4 v[4:7], v[12:13], off offset:2048
	global_load_dwordx4 v[8:11], v[16:17], off offset:2048
	s_nop 0
	global_load_dwordx4 v[12:15], v[12:13], off offset:1024
	s_nop 0
	global_load_dwordx4 v[16:19], v[16:17], off offset:1024
	v_add_u32_e32 v164, 0, v20
	v_add_u32_e32 v165, 0, v21
	v_add_u32_e32 v166, 0, v22
	s_waitcnt vmcnt(1)
	ds_write_b128 v164, v[12:15] offset:32768
	s_waitcnt vmcnt(0)
	ds_write_b128 v164, v[16:19] offset:40960
	ds_write_b128 v165, v[4:7]
	v_add_u32_e32 v4, 64, v158
	v_add_u32_e32 v6, 0x60, v158
	v_mad_i64_i32 v[4:5], s[0:1], v4, s33, v[2:3]
	v_mad_i64_i32 v[2:3], s[0:1], v6, s33, v[2:3]
	v_lshl_add_u64 v[4:5], v[4:5], 0, v[50:51]
	v_lshl_add_u64 v[2:3], v[2:3], 0, v[50:51]
	ds_write_b128 v166, v[8:11]
	s_waitcnt lgkmcnt(0)
	s_barrier
	global_load_dwordx4 v[34:37], v[4:5], off offset:2048
	global_load_dwordx4 v[38:41], v[2:3], off offset:2048
	global_load_dwordx4 v[42:45], v[4:5], off offset:1024
	global_load_dwordx4 v[46:49], v[2:3], off offset:1024
	v_lshlrev_b32_e32 v148, 4, v150
	s_add_i32 s2, s2, 0
	s_movk_i32 s0, 0xf0
	v_lshlrev_b32_e32 v51, 8, v151
	v_xor_b32_e32 v162, s2, v162
	v_bitop3_b32 v2, v162, v148, s0 bitop3:0x78
	v_add_u32_e32 v159, v51, v2
	ds_read_b128 v[2:5], v159 offset:32768
	v_and_b32_e32 v53, 0xf0, v148
	v_bitop3_b32 v6, v162, v53, 32 bitop3:0x36
	v_add_u32_e32 v160, v51, v6
	ds_read_b128 v[54:57], v160 offset:32768
	v_bitop3_b32 v58, v162, v53, 64 bitop3:0x36
	s_waitcnt lgkmcnt(1)
	v_mfma_f32_32x32x16_bf16 v[18:33], v[2:5], v[110:113], 0
	ds_read_b128 v[2:5], v159 offset:40960
	v_add_u32_e32 v161, v51, v58
	s_movk_i32 s0, 0x60
	v_bitop3_b32 v53, v162, v53, s0 bitop3:0x36
	v_add_u32_e32 v162, v51, v53
	s_cmp_gt_i32 s25, 62
	s_waitcnt lgkmcnt(1)
	v_mfma_f32_32x32x16_bf16 v[18:33], v[54:57], v[106:109], v[18:33]
	ds_read_b128 v[54:57], v160 offset:40960
	s_waitcnt lgkmcnt(1)
	v_mfma_f32_32x32x16_bf16 v[2:17], v[2:5], v[110:113], 0
	s_waitcnt lgkmcnt(0)
	v_mfma_f32_32x32x16_bf16 v[2:17], v[54:57], v[106:109], v[2:17]
	ds_read_b128 v[54:57], v161 offset:32768
	s_waitcnt lgkmcnt(0)
	v_mfma_f32_32x32x16_bf16 v[18:33], v[54:57], v[102:105], v[18:33]
	ds_read_b128 v[54:57], v161 offset:40960
	s_waitcnt lgkmcnt(0)
	v_mfma_f32_32x32x16_bf16 v[2:17], v[54:57], v[102:105], v[2:17]
	ds_read_b128 v[54:57], v162 offset:32768
	s_waitcnt lgkmcnt(0)
	v_mfma_f32_32x32x16_bf16 v[18:33], v[54:57], v[98:101], v[18:33]
	ds_read_b128 v[54:57], v162 offset:40960
	s_waitcnt lgkmcnt(0)
	v_mfma_f32_32x32x16_bf16 v[2:17], v[54:57], v[98:101], v[2:17]
	s_cbranch_scc1 .LBB0_821
	v_cmp_gt_i32_e64 s[90:91], 26, v156
	v_cmp_gt_i32_e64 s[92:93], 27, v156
	v_cmp_gt_i32_e64 s[88:89], 25, v156
	s_and_b64 s[90:91], s[92:93], s[90:91]
	v_cmp_gt_i32_e64 s[86:87], 24, v156
	s_and_b64 s[88:89], s[90:91], s[88:89]
	v_cmp_gt_i32_e64 s[84:85], 19, v156
	s_and_b64 s[86:87], s[88:89], s[86:87]
	v_cmp_gt_i32_e64 s[82:83], 18, v156
	s_and_b64 s[84:85], s[86:87], s[84:85]
	v_cmp_gt_i32_e64 s[80:81], 17, v156
	s_and_b64 s[82:83], s[84:85], s[82:83]
	v_cmp_gt_i32_e64 s[78:79], 16, v156
	s_and_b64 s[80:81], s[82:83], s[80:81]
	v_cmp_gt_i32_e64 s[76:77], 11, v156
	s_and_b64 s[78:79], s[80:81], s[78:79]
	v_cmp_gt_i32_e64 s[74:75], 10, v156
	s_and_b64 s[76:77], s[78:79], s[76:77]
	v_cmp_gt_i32_e64 s[72:73], 9, v156
	s_and_b64 s[74:75], s[76:77], s[74:75]
	v_cmp_gt_i32_e64 s[70:71], 8, v156
	s_and_b64 s[72:73], s[74:75], s[72:73]
	v_cmp_gt_i32_e64 s[68:69], 3, v156
	s_and_b64 s[70:71], s[72:73], s[70:71]
	v_cmp_gt_i32_e64 s[66:67], 2, v156
	s_and_b64 s[68:69], s[70:71], s[68:69]
	v_cmp_gt_i32_e64 s[2:3], 1, v156
	s_and_b64 s[66:67], s[68:69], s[66:67]
	v_cmp_gt_i32_e64 s[0:1], 0, v156
	s_and_b64 s[2:3], s[66:67], s[2:3]
	s_and_b64 s[0:1], s[2:3], s[0:1]
	v_cmp_gt_i32_e64 s[64:65], 58, v156
	v_cndmask_b32_e64 v18, v18, v175, s[0:1]
	v_cmp_gt_i32_e64 s[0:1], 59, v156
	v_cmp_gt_i32_e64 s[62:63], 57, v156
	v_cmp_gt_i32_e64 s[60:61], 56, v156
	v_cndmask_b32_e64 v17, v17, v175, s[0:1]
	s_and_b64 s[0:1], s[0:1], s[64:65]
	v_cndmask_b32_e64 v16, v16, v175, s[0:1]
	s_and_b64 s[0:1], s[0:1], s[62:63]
	v_cmp_gt_i32_e64 s[58:59], 51, v156
	v_cndmask_b32_e64 v15, v15, v175, s[0:1]
	s_and_b64 s[0:1], s[0:1], s[60:61]
	v_cmp_gt_i32_e64 s[56:57], 50, v156
	v_cndmask_b32_e64 v14, v14, v175, s[0:1]
	s_and_b64 s[0:1], s[0:1], s[58:59]
	v_cmp_gt_i32_e64 s[54:55], 49, v156
	v_cndmask_b32_e64 v13, v13, v175, s[0:1]
	s_and_b64 s[0:1], s[0:1], s[56:57]
	v_cmp_gt_i32_e64 s[52:53], 48, v156
	v_cndmask_b32_e64 v12, v12, v175, s[0:1]
	s_and_b64 s[0:1], s[0:1], s[54:55]
	v_cmp_gt_i32_e64 s[50:51], 43, v156
	v_cndmask_b32_e64 v11, v11, v175, s[0:1]
	s_and_b64 s[0:1], s[0:1], s[52:53]
	v_cmp_gt_i32_e64 s[48:49], 42, v156
	v_cndmask_b32_e64 v10, v10, v175, s[0:1]
	s_and_b64 s[0:1], s[0:1], s[50:51]
	v_cmp_gt_i32_e64 s[46:47], 41, v156
	v_cndmask_b32_e64 v9, v9, v175, s[0:1]
	s_and_b64 s[0:1], s[0:1], s[48:49]
	v_cmp_gt_i32_e64 s[44:45], 40, v156
	v_cndmask_b32_e64 v8, v8, v175, s[0:1]
	s_and_b64 s[0:1], s[0:1], s[46:47]
	v_cmp_gt_i32_e64 s[42:43], 35, v156
	v_cndmask_b32_e64 v7, v7, v175, s[0:1]
	s_and_b64 s[0:1], s[0:1], s[44:45]
	v_cmp_gt_i32_e64 s[40:41], 34, v156
	v_cndmask_b32_e64 v6, v6, v175, s[0:1]
	s_and_b64 s[0:1], s[0:1], s[42:43]
	v_cmp_gt_i32_e64 s[38:39], 33, v156
	v_cndmask_b32_e64 v5, v5, v175, s[0:1]
	s_and_b64 s[0:1], s[0:1], s[40:41]
	v_cmp_gt_i32_e32 vcc, 32, v156
	v_cndmask_b32_e64 v4, v4, v175, s[0:1]
	s_and_b64 s[0:1], s[0:1], s[38:39]
	s_and_b64 vcc, s[0:1], vcc
	v_cndmask_b32_e64 v33, v33, v175, s[92:93]
	v_cndmask_b32_e64 v32, v32, v175, s[90:91]
	v_cndmask_b32_e64 v31, v31, v175, s[88:89]
	v_cndmask_b32_e64 v30, v30, v175, s[86:87]
	v_cndmask_b32_e64 v29, v29, v175, s[84:85]
	v_cndmask_b32_e64 v28, v28, v175, s[82:83]
	v_cndmask_b32_e64 v27, v27, v175, s[80:81]
	v_cndmask_b32_e64 v26, v26, v175, s[78:79]
	v_cndmask_b32_e64 v25, v25, v175, s[76:77]
	v_cndmask_b32_e64 v24, v24, v175, s[74:75]
	v_cndmask_b32_e64 v23, v23, v175, s[72:73]
	v_cndmask_b32_e64 v22, v22, v175, s[70:71]
	v_cndmask_b32_e64 v21, v21, v175, s[68:69]
	v_cndmask_b32_e64 v20, v20, v175, s[66:67]
	v_cndmask_b32_e64 v19, v19, v175, s[2:3]
	v_cndmask_b32_e64 v3, v3, v175, s[0:1]
	v_cndmask_b32_e32 v2, v2, v175, vcc

.Lmskip_dif_1:
	s_sub_i32 s0, s9, s25
	s_cmp_ge_i32 s0, 95
	s_cbranch_scc1 .Lp1skip_dif_1
	s_cmp_le_i32 s9, s25
	s_cbranch_scc1 .LBB0_825
	v_add_u32_e32 v132, 64, v169
	v_cmp_gt_i32_e64 s[92:93], 26, v132
	v_cmp_gt_i32_e64 s[94:95], 27, v132
	v_cmp_gt_i32_e64 s[90:91], 25, v132
	s_and_b64 s[92:93], s[94:95], s[92:93]
	v_cmp_gt_i32_e64 s[88:89], 24, v132
	s_and_b64 s[90:91], s[92:93], s[90:91]
	v_cmp_gt_i32_e64 s[86:87], 19, v132
	s_and_b64 s[88:89], s[90:91], s[88:89]
	v_cmp_gt_i32_e64 s[84:85], 18, v132
	s_and_b64 s[86:87], s[88:89], s[86:87]
	v_cmp_gt_i32_e64 s[82:83], 17, v132
	s_and_b64 s[84:85], s[86:87], s[84:85]
	v_cmp_gt_i32_e64 s[80:81], 16, v132
	s_and_b64 s[82:83], s[84:85], s[82:83]
	v_cmp_gt_i32_e64 s[78:79], 11, v132
	s_and_b64 s[80:81], s[82:83], s[80:81]
	v_cmp_gt_i32_e64 s[76:77], 10, v132
	s_and_b64 s[78:79], s[80:81], s[78:79]
	v_cmp_gt_i32_e64 s[74:75], 9, v132
	s_and_b64 s[76:77], s[78:79], s[76:77]
	v_cmp_gt_i32_e64 s[72:73], 8, v132
	s_and_b64 s[74:75], s[76:77], s[74:75]
	v_cmp_gt_i32_e64 s[70:71], 3, v132
	s_and_b64 s[72:73], s[74:75], s[72:73]
	v_cmp_gt_i32_e64 s[68:69], 2, v132
	s_and_b64 s[70:71], s[72:73], s[70:71]
	v_cmp_gt_i32_e64 s[2:3], 1, v132
	s_and_b64 s[68:69], s[70:71], s[68:69]
	v_cmp_gt_i32_e64 s[0:1], 0, v132
	s_and_b64 s[2:3], s[68:69], s[2:3]
	s_and_b64 s[0:1], s[2:3], s[0:1]
	v_cmp_gt_i32_e64 s[66:67], 58, v132
	v_cndmask_b32_e64 v82, v82, v175, s[0:1]
	v_cmp_gt_i32_e64 s[0:1], 59, v132
	v_cmp_gt_i32_e64 s[64:65], 57, v132
	v_cmp_gt_i32_e64 s[62:63], 56, v132
	v_cndmask_b32_e64 v81, v81, v175, s[0:1]
	s_and_b64 s[0:1], s[0:1], s[66:67]
	v_cndmask_b32_e64 v80, v80, v175, s[0:1]
	s_and_b64 s[0:1], s[0:1], s[64:65]
	v_cmp_gt_i32_e64 s[60:61], 51, v132
	v_cndmask_b32_e64 v79, v79, v175, s[0:1]
	s_and_b64 s[0:1], s[0:1], s[62:63]
	v_cmp_gt_i32_e64 s[58:59], 50, v132
	v_cndmask_b32_e64 v78, v78, v175, s[0:1]
	s_and_b64 s[0:1], s[0:1], s[60:61]
	v_cmp_gt_i32_e64 s[56:57], 49, v132
	v_cndmask_b32_e64 v77, v77, v175, s[0:1]
	s_and_b64 s[0:1], s[0:1], s[58:59]
	v_cmp_gt_i32_e64 s[54:55], 48, v132
	v_cndmask_b32_e64 v76, v76, v175, s[0:1]
	s_and_b64 s[0:1], s[0:1], s[56:57]
	v_cmp_gt_i32_e64 s[52:53], 43, v132
	v_cndmask_b32_e64 v75, v75, v175, s[0:1]
	s_and_b64 s[0:1], s[0:1], s[54:55]
	v_cmp_gt_i32_e64 s[50:51], 42, v132
	v_cndmask_b32_e64 v74, v74, v175, s[0:1]
	s_and_b64 s[0:1], s[0:1], s[52:53]
	v_cmp_gt_i32_e64 s[48:49], 41, v132
	v_cndmask_b32_e64 v73, v73, v175, s[0:1]
	s_and_b64 s[0:1], s[0:1], s[50:51]
	v_cmp_gt_i32_e64 s[46:47], 40, v132
	v_cndmask_b32_e64 v72, v72, v175, s[0:1]
	s_and_b64 s[0:1], s[0:1], s[48:49]
	v_cmp_gt_i32_e64 s[44:45], 35, v132
	v_cndmask_b32_e64 v71, v71, v175, s[0:1]
	s_and_b64 s[0:1], s[0:1], s[46:47]
	v_cmp_gt_i32_e64 s[42:43], 34, v132
	v_cndmask_b32_e64 v70, v70, v175, s[0:1]
	s_and_b64 s[0:1], s[0:1], s[44:45]
	v_cmp_gt_i32_e64 s[40:41], 33, v132
	v_cndmask_b32_e64 v69, v69, v175, s[0:1]
	s_and_b64 s[0:1], s[0:1], s[42:43]
	v_cmp_gt_i32_e32 vcc, 32, v132
	v_cndmask_b32_e64 v68, v68, v175, s[0:1]
	s_and_b64 s[0:1], s[0:1], s[40:41]
	s_and_b64 vcc, s[0:1], vcc
	v_cndmask_b32_e64 v97, v97, v175, s[94:95]
	v_cndmask_b32_e64 v96, v96, v175, s[92:93]
	v_cndmask_b32_e64 v95, v95, v175, s[90:91]
	v_cndmask_b32_e64 v94, v94, v175, s[88:89]
	v_cndmask_b32_e64 v93, v93, v175, s[86:87]
	v_cndmask_b32_e64 v92, v92, v175, s[84:85]
	v_cndmask_b32_e64 v91, v91, v175, s[82:83]
	v_cndmask_b32_e64 v90, v90, v175, s[80:81]
	v_cndmask_b32_e64 v89, v89, v175, s[78:79]
	v_cndmask_b32_e64 v88, v88, v175, s[76:77]
	v_cndmask_b32_e64 v87, v87, v175, s[74:75]
	v_cndmask_b32_e64 v86, v86, v175, s[72:73]
	v_cndmask_b32_e64 v85, v85, v175, s[70:71]
	v_cndmask_b32_e64 v84, v84, v175, s[68:69]
	v_cndmask_b32_e64 v83, v83, v175, s[2:3]
	v_cndmask_b32_e64 v67, v67, v175, s[0:1]
	v_cndmask_b32_e32 v66, v66, v175, vcc

.Lp1join_dif_1:
	v_cmp_gt_f32_e32 vcc, 1.0, v181
	s_barrier
	s_waitcnt vmcnt(2)
	ds_write_b128 v164, v[122:125] offset:32768
	s_waitcnt vmcnt(0)
	ds_write_b128 v164, v[126:129] offset:40960
	ds_write_b128 v165, v[114:117]
	ds_write_b128 v166, v[118:121]
	s_cbranch_vccz .LBB0_829
	s_and_saveexec_b64 s[0:1], s[38:39]
	ds_write_b32 v155, v181 offset:128
	s_or_b64 exec, exec, s[0:1]
	s_waitcnt lgkmcnt(0)
	ds_read_b128 v[134:137], v154 offset:224
	ds_read_b128 v[138:141], v154 offset:192
	ds_read_b128 v[142:145], v154 offset:160
	ds_read_b128 v[184:187], v154 offset:128
	s_waitcnt lgkmcnt(3)
	v_mul_f32 v64, v64, v136
	v_mul_f32 v65, v65, v137
	s_waitcnt lgkmcnt(2)
	v_mul_f32 v60, v60, v140
	v_mul_f32 v61, v61, v141
	s_waitcnt lgkmcnt(1)
	v_mul_f32 v56, v56, v144
	v_mul_f32 v57, v57, v145
	s_waitcnt lgkmcnt(0)
	v_mul_f32 v52, v52, v186
	v_mul_f32 v53, v53, v187
	v_mul_f32 v62, v62, v134
	v_mul_f32 v63, v63, v135
	v_mul_f32 v58, v58, v138
	v_mul_f32 v59, v59, v139
	v_mul_f32 v54, v54, v142
	v_mul_f32 v55, v55, v143
	v_mul_f32 v50, v50, v184
	v_mul_f32 v51, v51, v185
	v_mul_f32 v48, v48, v136
	v_mul_f32 v49, v49, v137
	v_mul_f32 v44, v44, v140
	v_mul_f32 v45, v45, v141
	v_mul_f32 v40, v40, v144
	v_mul_f32 v41, v41, v145
	v_mul_f32 v36, v36, v186
	v_mul_f32 v37, v37, v187
	v_mul_f32 v46, v46, v134
	v_mul_f32 v47, v47, v135
	v_mul_f32 v42, v42, v138
	v_mul_f32 v43, v43, v139
	v_mul_f32 v38, v38, v142
	v_mul_f32 v39, v39, v143
	v_mul_f32 v34, v34, v184
	v_mul_f32 v35, v35, v185
	v_mul_f32 v32, v32, v136
	v_mul_f32 v33, v33, v137
	v_mul_f32 v28, v28, v140
	v_mul_f32 v29, v29, v141
	v_mul_f32 v24, v24, v144
	v_mul_f32 v25, v25, v145
	v_mul_f32 v20, v20, v186
	v_mul_f32 v21, v21, v187
	v_mul_f32 v30, v30, v134
	v_mul_f32 v31, v31, v135
	v_mul_f32 v26, v26, v138
	v_mul_f32 v27, v27, v139
	v_mul_f32 v22, v22, v142
	v_mul_f32 v23, v23, v143
	v_mul_f32 v18, v18, v184
	v_mul_f32 v19, v19, v185
	v_mul_f32 v16, v16, v136
	v_mul_f32 v17, v17, v137
	v_mul_f32 v12, v12, v140
	v_mul_f32 v13, v13, v141
	v_mul_f32 v8, v8, v144
	v_mul_f32 v9, v9, v145
	v_mul_f32 v4, v4, v186
	v_mul_f32 v5, v5, v187
	v_mul_f32 v14, v14, v134
	v_mul_f32 v15, v15, v135
	v_mul_f32 v10, v10, v138
	v_mul_f32 v11, v11, v139
	v_mul_f32 v6, v6, v142
	v_mul_f32 v7, v7, v143
	v_mul_f32 v2, v2, v184
	v_mul_f32 v3, v3, v185

.Lmskip_dif_3:
	s_sub_i32 s0, s9, s25
	s_cmp_ge_i32 s0, 31
	s_cbranch_scc1 .Lp1skip_dif_3
	s_add_i32 s0, s9, 64
	s_cmp_le_i32 s0, s25
	s_cbranch_scc1 .LBB0_833
	v_cmp_gt_i32_e64 s[92:93], 26, v169
	v_cmp_gt_i32_e64 s[94:95], 27, v169
	v_cmp_gt_i32_e64 s[90:91], 25, v169
	s_and_b64 s[92:93], s[94:95], s[92:93]
	v_cmp_gt_i32_e64 s[88:89], 24, v169
	s_and_b64 s[90:91], s[92:93], s[90:91]
	v_cmp_gt_i32_e64 s[86:87], 19, v169
	s_and_b64 s[88:89], s[90:91], s[88:89]
	v_cmp_gt_i32_e64 s[84:85], 18, v169
	s_and_b64 s[86:87], s[88:89], s[86:87]
	v_cmp_gt_i32_e64 s[82:83], 17, v169
	s_and_b64 s[84:85], s[86:87], s[84:85]
	v_cmp_gt_i32_e64 s[80:81], 16, v169
	s_and_b64 s[82:83], s[84:85], s[82:83]
	v_cmp_gt_i32_e64 s[78:79], 11, v169
	s_and_b64 s[80:81], s[82:83], s[80:81]
	v_cmp_gt_i32_e64 s[76:77], 10, v169
	s_and_b64 s[78:79], s[80:81], s[78:79]
	v_cmp_gt_i32_e64 s[74:75], 9, v169
	s_and_b64 s[76:77], s[78:79], s[76:77]
	v_cmp_gt_i32_e64 s[72:73], 8, v169
	s_and_b64 s[74:75], s[76:77], s[74:75]
	v_cmp_gt_i32_e64 s[70:71], 3, v169
	s_and_b64 s[72:73], s[74:75], s[72:73]
	v_cmp_gt_i32_e64 s[68:69], 2, v169
	s_and_b64 s[70:71], s[72:73], s[70:71]
	v_cmp_gt_i32_e64 s[2:3], 1, v169
	s_and_b64 s[68:69], s[70:71], s[68:69]
	v_cmp_gt_i32_e64 s[0:1], 0, v169
	s_and_b64 s[2:3], s[68:69], s[2:3]
	s_and_b64 s[0:1], s[2:3], s[0:1]
	v_cmp_gt_i32_e64 s[66:67], 58, v169
	v_cndmask_b32_e64 v82, v82, v175, s[0:1]
	v_cmp_gt_i32_e64 s[0:1], 59, v169
	v_cmp_gt_i32_e64 s[64:65], 57, v169
	v_cmp_gt_i32_e64 s[62:63], 56, v169
	v_cndmask_b32_e64 v81, v81, v175, s[0:1]
	s_and_b64 s[0:1], s[0:1], s[66:67]
	v_cndmask_b32_e64 v80, v80, v175, s[0:1]
	s_and_b64 s[0:1], s[0:1], s[64:65]
	v_cmp_gt_i32_e64 s[60:61], 51, v169
	v_cndmask_b32_e64 v79, v79, v175, s[0:1]
	s_and_b64 s[0:1], s[0:1], s[62:63]
	v_cmp_gt_i32_e64 s[58:59], 50, v169
	v_cndmask_b32_e64 v78, v78, v175, s[0:1]
	s_and_b64 s[0:1], s[0:1], s[60:61]
	v_cmp_gt_i32_e64 s[56:57], 49, v169
	v_cndmask_b32_e64 v77, v77, v175, s[0:1]
	s_and_b64 s[0:1], s[0:1], s[58:59]
	v_cmp_gt_i32_e64 s[54:55], 48, v169
	v_cndmask_b32_e64 v76, v76, v175, s[0:1]
	s_and_b64 s[0:1], s[0:1], s[56:57]
	v_cmp_gt_i32_e64 s[52:53], 43, v169
	v_cndmask_b32_e64 v75, v75, v175, s[0:1]
	s_and_b64 s[0:1], s[0:1], s[54:55]
	v_cmp_gt_i32_e64 s[50:51], 42, v169
	v_cndmask_b32_e64 v74, v74, v175, s[0:1]
	s_and_b64 s[0:1], s[0:1], s[52:53]
	v_cmp_gt_i32_e64 s[48:49], 41, v169
	v_cndmask_b32_e64 v73, v73, v175, s[0:1]
	s_and_b64 s[0:1], s[0:1], s[50:51]
	v_cmp_gt_i32_e64 s[46:47], 40, v169
	v_cndmask_b32_e64 v72, v72, v175, s[0:1]
	s_and_b64 s[0:1], s[0:1], s[48:49]
	v_cmp_gt_i32_e64 s[44:45], 35, v169
	v_cndmask_b32_e64 v71, v71, v175, s[0:1]
	s_and_b64 s[0:1], s[0:1], s[46:47]
	v_cmp_gt_i32_e64 s[42:43], 34, v169
	v_cndmask_b32_e64 v70, v70, v175, s[0:1]
	s_and_b64 s[0:1], s[0:1], s[44:45]
	v_cmp_gt_i32_e64 s[40:41], 33, v169
	v_cndmask_b32_e64 v69, v69, v175, s[0:1]
	s_and_b64 s[0:1], s[0:1], s[42:43]
	v_cmp_gt_i32_e32 vcc, 32, v169
	v_cndmask_b32_e64 v68, v68, v175, s[0:1]
	s_and_b64 s[0:1], s[0:1], s[40:41]
	s_and_b64 vcc, s[0:1], vcc
	v_cndmask_b32_e64 v97, v97, v175, s[94:95]
	v_cndmask_b32_e64 v96, v96, v175, s[92:93]
	v_cndmask_b32_e64 v95, v95, v175, s[90:91]
	v_cndmask_b32_e64 v94, v94, v175, s[88:89]
	v_cndmask_b32_e64 v93, v93, v175, s[86:87]
	v_cndmask_b32_e64 v92, v92, v175, s[84:85]
	v_cndmask_b32_e64 v91, v91, v175, s[82:83]
	v_cndmask_b32_e64 v90, v90, v175, s[80:81]
	v_cndmask_b32_e64 v89, v89, v175, s[78:79]
	v_cndmask_b32_e64 v88, v88, v175, s[76:77]
	v_cndmask_b32_e64 v87, v87, v175, s[74:75]
	v_cndmask_b32_e64 v86, v86, v175, s[72:73]
	v_cndmask_b32_e64 v85, v85, v175, s[70:71]
	v_cndmask_b32_e64 v84, v84, v175, s[68:69]
	v_cndmask_b32_e64 v83, v83, v175, s[2:3]
	v_cndmask_b32_e64 v67, v67, v175, s[0:1]
	v_cndmask_b32_e32 v66, v66, v175, vcc

.Lp1join_dif_3:
	s_andn2_b64 vcc, exec, s[22:23]
	s_barrier
	s_cbranch_vccnz .LBB0_835
	s_waitcnt vmcnt(2)
	ds_write_b128 v164, v[122:125] offset:49152
	s_waitcnt vmcnt(0)
	ds_write_b128 v164, v[126:129] offset:57344
	ds_write_b128 v165, v[114:117] offset:16384
	ds_write_b128 v166, v[118:121] offset:16384

.Lp1skip_dif_1:
	v_mov_b32_e32 v181, 1.0
	s_mov_b64 s[40:41], -1
	s_branch .Lp1join_dif_1
